# prompt attention: K tile via LDS-DMA + V loads hoisted to half-step start in loop A (both half-steps) and first half-step of loops B and C
# baseline (speedup 1.0000x reference)
.LBB0_1354:
	v_readfirstlane_b32 s8, v183
	v_lshrrev_b32_e32 v234, 4, v183
	v_lshl_add_u64 v[230:231], v[170:171], 0, v[96:97]
	s_mov_b32 s10, 0x14b40000
	s_mov_b32 s11, 0
	s_and_b32 s8, s8, 0xfffffc00
	v_and_b32_e32 v234, 0x70, v234
	v_lshl_add_u64 v[230:231], v[230:231], 0, s[10:11]
	s_add_i32 m0, s8, 0x8000
	v_xor_b32_e32 v230, v234, v230
	v_lshl_add_u64 v[242:243], v[168:169], 0, v[96:97]
	s_mov_b32 s10, 0x10000
	global_load_lds_dwordx4 v[230:231], off
	v_lshl_add_u64 v[230:231], v[230:231], 0, s[10:11]
	s_add_i32 m0, s8, 0xa000
	s_mov_b32 s10, 0x15c40000
	v_lshl_add_u64 v[242:243], v[242:243], 0, s[10:11]
	global_load_lds_dwordx4 v[230:231], off
	s_mov_b32 s10, 0x10000
	v_lshl_add_u64 v[246:247], v[242:243], 0, s[10:11]
	global_load_dwordx4 v[242:245], v[242:243], off
	global_load_dwordx4 v[246:249], v[246:247], off
	ds_read_b128 v[80:83], v193
	ds_read_b128 v[84:87], v193 offset:32
	ds_read_b128 v[64:67], v193 offset:128
	ds_read_b128 v[68:71], v193 offset:160
	ds_read_b128 v[88:91], v193 offset:64
	ds_read_b128 v[72:75], v193 offset:192
	ds_read_b128 v[92:95], v193 offset:96
	ds_read_b128 v[76:79], v193 offset:224
	ds_read_b128 v[130:133], v187 offset:49152
	s_waitcnt vmcnt(2)
	ds_read_b128 v[134:137], v187 offset:57344
	s_waitcnt vmcnt(1)
	v_exp_f32_e32 v138, v146
	v_add_f32_e32 v146, 0, v203
	v_add_f32_e32 v146, v204, v146
	s_waitcnt lgkmcnt(1)
	v_mfma_f32_32x32x16_bf16 v[80:95], v[130:133], v[126:129], v[80:95]
	v_add_f32_e32 v146, v205, v146
	v_add_f32_e32 v146, v207, v146
	v_add_f32_e32 v146, v208, v146
	v_add_f32_e32 v146, v210, v146
	v_add_f32_e32 v146, v206, v146
	v_add_f32_e32 v146, v209, v146
	v_add_f32_e32 v146, v173, v146
	s_waitcnt lgkmcnt(0)
	v_mfma_f32_32x32x16_bf16 v[64:79], v[134:137], v[126:129], v[64:79]
	ds_read_b128 v[130:133], v188 offset:49152
	ds_read_b128 v[134:137], v188 offset:57344
	v_add_f32_e32 v146, v175, v146
	v_add_f32_e32 v146, v198, v146
	v_add_f32_e32 v146, v201, v146
	v_add_f32_e32 v146, v174, v146
	v_add_f32_e32 v146, v199, v146
	v_add_f32_e32 v146, v200, v146
	s_waitcnt lgkmcnt(1)
	v_mfma_f32_32x32x16_bf16 v[80:95], v[130:133], v[122:125], v[80:95]
	v_add_f32_e32 v146, v202, v146
	v_exp_f32_e32 v139, v147
	v_exp_f32_e32 v140, v160
	v_exp_f32_e32 v141, v161
	s_waitcnt vmcnt(0)
	v_exp_f32_e32 v142, v154
	v_exp_f32_e32 v143, v155
	v_exp_f32_e32 v144, v148
	s_waitcnt lgkmcnt(0)
	v_mfma_f32_32x32x16_bf16 v[64:79], v[134:137], v[122:125], v[64:79]
	ds_read_b128 v[130:133], v186 offset:49152
	ds_read_b128 v[134:137], v186 offset:57344
	v_exp_f32_e32 v145, v149
	v_cvt_pk_bf16_f32 v147, v205, v207
	v_cvt_pk_bf16_f32 v148, v208, v210
	v_cvt_pk_bf16_f32 v149, v206, v209
	v_cvt_pk_bf16_f32 v160, v142, v143
	v_cvt_pk_bf16_f32 v161, v144, v145
	s_waitcnt lgkmcnt(1)
	v_mfma_f32_32x32x16_bf16 v[80:95], v[130:133], v[118:121], v[80:95]
	v_permlane32_swap_b32_e32 v147, v149
	s_waitcnt lgkmcnt(0)
	v_mfma_f32_32x32x16_bf16 v[64:79], v[134:137], v[118:121], v[64:79]
	ds_read_b128 v[130:133], v167 offset:49152
	ds_read_b128 v[134:137], v167 offset:57344
	s_waitcnt lgkmcnt(1)
	v_mfma_f32_32x32x16_bf16 v[80:95], v[130:133], v[114:117], v[80:95]
	s_waitcnt lgkmcnt(0)
	v_mfma_f32_32x32x16_bf16 v[64:79], v[134:137], v[114:117], v[64:79]
	ds_read_b128 v[130:133], v187 offset:49280
	ds_read_b128 v[134:137], v187 offset:57472
	s_waitcnt lgkmcnt(1)
	v_mfma_f32_32x32x16_bf16 v[80:95], v[130:133], v[110:113], v[80:95]
	s_waitcnt lgkmcnt(0)
	v_mfma_f32_32x32x16_bf16 v[64:79], v[134:137], v[110:113], v[64:79]
	ds_read_b128 v[130:133], v188 offset:49280
	ds_read_b128 v[134:137], v188 offset:57472
	s_waitcnt lgkmcnt(1)
	v_mfma_f32_32x32x16_bf16 v[80:95], v[130:133], v[106:109], v[80:95]
	s_waitcnt lgkmcnt(0)
	v_mfma_f32_32x32x16_bf16 v[64:79], v[134:137], v[106:109], v[64:79]
	ds_read_b128 v[130:133], v186 offset:49280
	ds_read_b128 v[134:137], v186 offset:57472
	s_waitcnt lgkmcnt(1)
	v_mfma_f32_32x32x16_bf16 v[80:95], v[130:133], v[102:105], v[80:95]
	s_waitcnt lgkmcnt(0)
	v_mfma_f32_32x32x16_bf16 v[64:79], v[134:137], v[102:105], v[64:79]
	ds_read_b128 v[130:133], v167 offset:49280
	ds_read_b128 v[134:137], v167 offset:57472
	s_waitcnt lgkmcnt(1)
	v_mfma_f32_32x32x16_bf16 v[80:95], v[130:133], v[98:101], v[80:95]
	v_exp_f32_e32 v130, v158
	v_exp_f32_e32 v131, v159
	v_exp_f32_e32 v132, v156
	v_exp_f32_e32 v133, v157
	v_add_f32_e32 v146, v130, v146
	v_add_f32_e32 v146, v131, v146
	v_add_f32_e32 v146, v132, v146
	s_waitcnt lgkmcnt(0)
	v_mfma_f32_32x32x16_bf16 v[64:79], v[134:137], v[98:101], v[64:79]
	v_exp_f32_e32 v134, v152
	v_exp_f32_e32 v135, v153
	v_exp_f32_e32 v136, v150
	v_exp_f32_e32 v137, v151
	v_add_f32_e32 v146, v133, v146
	v_add_f32_e32 v146, v134, v146
	v_add_f32_e32 v146, v135, v146
	v_add_f32_e32 v146, v136, v146
	v_add_f32_e32 v146, v137, v146
	v_add_f32_e32 v146, v138, v146
	v_add_f32_e32 v146, v139, v146
	v_add_f32_e32 v146, v140, v146
	v_add_f32_e32 v146, v141, v146
	v_add_f32_e32 v146, v142, v146
	v_add_f32_e32 v146, v143, v146
	v_add_f32_e32 v146, v144, v146
	v_add_f32_e32 v195, v145, v146
	v_mov_b32_e32 v196, v195
	s_nop 1
	v_permlane32_swap_b32_e32 v195, v196
	v_cvt_pk_bf16_f32 v146, v203, v204
	v_cvt_pk_bf16_f32 v150, v173, v175
	v_cvt_pk_bf16_f32 v151, v198, v201
	v_cvt_pk_bf16_f32 v152, v174, v199
	v_cvt_pk_bf16_f32 v153, v200, v202
	v_cvt_pk_bf16_f32 v154, v130, v131
	v_cvt_pk_bf16_f32 v155, v132, v133
	v_cvt_pk_bf16_f32 v156, v134, v135
	v_cvt_pk_bf16_f32 v157, v136, v137
	v_cvt_pk_bf16_f32 v158, v138, v139
	v_cvt_pk_bf16_f32 v159, v140, v141
	v_permlane32_swap_b32_e32 v146, v148
	v_permlane32_swap_b32_e32 v150, v152
	v_permlane32_swap_b32_e32 v151, v153
	v_permlane32_swap_b32_e32 v154, v156
	v_permlane32_swap_b32_e32 v155, v157
	v_permlane32_swap_b32_e32 v158, v160
	v_permlane32_swap_b32_e32 v159, v161
	v_lshl_add_u64 v[174:175], v[168:169], 0, v[96:97]
	v_lshl_add_u64 v[172:173], v[170:171], 0, v[96:97]
	ds_read_b64_tr_b16 v[198:199], v180 offset:0
	ds_read_b64_tr_b16 v[200:201], v180 offset:0x800
	ds_read_b64_tr_b16 v[202:203], v180 offset:0x1000
	ds_read_b64_tr_b16 v[204:205], v180 offset:0x1800
	ds_read_b64_tr_b16 v[206:207], v180 offset:0x2000
	ds_read_b64_tr_b16 v[208:209], v180 offset:0x2800
	ds_read_b64_tr_b16 v[210:211], v180 offset:0x3000
	ds_read_b64_tr_b16 v[212:213], v180 offset:0x3800
	s_waitcnt lgkmcnt(0)
	s_nop 0
	v_mfma_f32_32x32x16_bf16 v[48:63], v[146:149], v[198:201], v[48:63]
	ds_read_b64_tr_b16 v[198:199], v180 offset:0x200
	ds_read_b64_tr_b16 v[200:201], v180 offset:0xa00
	v_mfma_f32_32x32x16_bf16 v[48:63], v[150:153], v[202:205], v[48:63]
	ds_read_b64_tr_b16 v[202:203], v180 offset:0x1200
	ds_read_b64_tr_b16 v[204:205], v180 offset:0x1a00
	v_mfma_f32_32x32x16_bf16 v[48:63], v[154:157], v[206:209], v[48:63]
	ds_read_b64_tr_b16 v[206:207], v180 offset:0x2200
	ds_read_b64_tr_b16 v[208:209], v180 offset:0x2a00
	v_mfma_f32_32x32x16_bf16 v[48:63], v[158:161], v[210:213], v[48:63]
	ds_read_b64_tr_b16 v[210:211], v180 offset:0x3200
	ds_read_b64_tr_b16 v[212:213], v180 offset:0x3a00
	s_waitcnt lgkmcnt(0)
	v_mfma_f32_32x32x16_bf16 v[32:47], v[146:149], v[198:201], v[32:47]
	ds_read_b64_tr_b16 v[198:199], v180 offset:0x400
	ds_read_b64_tr_b16 v[200:201], v180 offset:0xc00
	v_mfma_f32_32x32x16_bf16 v[32:47], v[150:153], v[202:205], v[32:47]
	ds_read_b64_tr_b16 v[202:203], v180 offset:0x1400
	ds_read_b64_tr_b16 v[204:205], v180 offset:0x1c00
	v_mfma_f32_32x32x16_bf16 v[32:47], v[154:157], v[206:209], v[32:47]
	ds_read_b64_tr_b16 v[206:207], v180 offset:0x2400
	ds_read_b64_tr_b16 v[208:209], v180 offset:0x2c00
	v_mfma_f32_32x32x16_bf16 v[32:47], v[158:161], v[210:213], v[32:47]
	ds_read_b64_tr_b16 v[210:211], v180 offset:0x3400
	ds_read_b64_tr_b16 v[212:213], v180 offset:0x3c00
	s_waitcnt lgkmcnt(0)
	v_mfma_f32_32x32x16_bf16 v[16:31], v[146:149], v[198:201], v[16:31]
	ds_read_b64_tr_b16 v[198:199], v180 offset:0x600
	ds_read_b64_tr_b16 v[200:201], v180 offset:0xe00
	v_mfma_f32_32x32x16_bf16 v[16:31], v[150:153], v[202:205], v[16:31]
	ds_read_b64_tr_b16 v[202:203], v180 offset:0x1600
	ds_read_b64_tr_b16 v[204:205], v180 offset:0x1e00
	v_mfma_f32_32x32x16_bf16 v[16:31], v[154:157], v[206:209], v[16:31]
	ds_read_b64_tr_b16 v[206:207], v180 offset:0x2600
	ds_read_b64_tr_b16 v[208:209], v180 offset:0x2e00
	v_mfma_f32_32x32x16_bf16 v[16:31], v[158:161], v[210:213], v[16:31]
	ds_read_b64_tr_b16 v[210:211], v180 offset:0x3600
	ds_read_b64_tr_b16 v[212:213], v180 offset:0x3e00
	s_waitcnt lgkmcnt(0)
	v_mfma_f32_32x32x16_bf16 v[0:15], v[146:149], v[198:201], v[0:15]
	s_sub_i32 s6, s92, 64
	s_cmp_le_i32 s6, s41
	v_mfma_f32_32x32x16_bf16 v[0:15], v[150:153], v[202:205], v[0:15]
	v_mfma_f32_32x32x16_bf16 v[0:15], v[154:157], v[206:209], v[0:15]
	v_mfma_f32_32x32x16_bf16 v[0:15], v[158:161], v[210:213], v[0:15]
	s_cbranch_scc1 .LBB0_1356
	v_add_u32_e32 v146, 64, v192
	v_cmp_gt_i32_e64 s[66:67], 26, v146
	v_cmp_gt_i32_e64 s[68:69], 27, v146
	v_cmp_gt_i32_e64 s[64:65], 25, v146
	s_and_b64 s[66:67], s[68:69], s[66:67]
	v_cmp_gt_i32_e64 s[62:63], 24, v146
	s_and_b64 s[64:65], s[66:67], s[64:65]
	v_cmp_gt_i32_e64 s[60:61], 19, v146
	s_and_b64 s[62:63], s[64:65], s[62:63]
	v_cmp_gt_i32_e64 s[58:59], 18, v146
	s_and_b64 s[60:61], s[62:63], s[60:61]
	v_cmp_gt_i32_e64 s[56:57], 17, v146
	s_and_b64 s[58:59], s[60:61], s[58:59]
	v_cmp_gt_i32_e64 s[54:55], 16, v146
	s_and_b64 s[56:57], s[58:59], s[56:57]
	v_cmp_gt_i32_e64 s[52:53], 11, v146
	s_and_b64 s[54:55], s[56:57], s[54:55]
	v_cmp_gt_i32_e64 s[50:51], 10, v146
	s_and_b64 s[52:53], s[54:55], s[52:53]
	v_cmp_gt_i32_e64 s[48:49], 9, v146
	s_and_b64 s[50:51], s[52:53], s[50:51]
	v_cmp_gt_i32_e64 s[46:47], 8, v146
	s_and_b64 s[48:49], s[50:51], s[48:49]
	v_cmp_gt_i32_e64 s[44:45], 3, v146
	s_and_b64 s[46:47], s[48:49], s[46:47]
	v_cmp_gt_i32_e64 s[42:43], 2, v146
	s_and_b64 s[44:45], s[46:47], s[44:45]
	v_cmp_gt_i32_e64 s[38:39], 1, v146
	s_and_b64 s[42:43], s[44:45], s[42:43]
	v_cmp_gt_i32_e64 s[36:37], 0, v146
	s_and_b64 s[38:39], s[42:43], s[38:39]
	s_and_b64 s[36:37], s[38:39], s[36:37]
	v_cmp_gt_i32_e64 s[34:35], 58, v146
	v_cndmask_b32_e64 v80, v80, v232, s[36:37]
	v_cmp_gt_i32_e64 s[36:37], 59, v146
	v_cmp_gt_i32_e64 s[30:31], 57, v146
	s_and_b64 s[34:35], s[36:37], s[34:35]
	v_cmp_gt_i32_e64 s[28:29], 56, v146
	s_and_b64 s[30:31], s[34:35], s[30:31]
	v_cmp_gt_i32_e64 s[26:27], 51, v146
	s_and_b64 s[28:29], s[30:31], s[28:29]
	v_cmp_gt_i32_e64 s[24:25], 50, v146
	s_and_b64 s[26:27], s[28:29], s[26:27]
	v_cmp_gt_i32_e64 s[22:23], 49, v146
	s_and_b64 s[24:25], s[26:27], s[24:25]
	v_cmp_gt_i32_e64 s[20:21], 48, v146
	s_and_b64 s[22:23], s[24:25], s[22:23]
	v_cmp_gt_i32_e64 s[18:19], 43, v146
	s_and_b64 s[20:21], s[22:23], s[20:21]
	v_cmp_gt_i32_e64 s[16:17], 42, v146
	s_and_b64 s[18:19], s[20:21], s[18:19]
	v_cmp_gt_i32_e64 s[14:15], 41, v146
	s_and_b64 s[16:17], s[18:19], s[16:17]
	v_cmp_gt_i32_e64 s[12:13], 40, v146
	s_and_b64 s[14:15], s[16:17], s[14:15]
	v_cmp_gt_i32_e64 s[10:11], 35, v146
	s_and_b64 s[12:13], s[14:15], s[12:13]
	v_cmp_gt_i32_e64 s[8:9], 34, v146
	s_and_b64 s[10:11], s[12:13], s[10:11]
	v_cmp_gt_i32_e64 s[6:7], 33, v146
	s_and_b64 s[8:9], s[10:11], s[8:9]
	v_cmp_gt_i32_e32 vcc, 32, v146
	s_and_b64 s[6:7], s[8:9], s[6:7]
	s_and_b64 vcc, s[6:7], vcc
	v_cndmask_b32_e64 v95, v95, v232, s[68:69]
	v_cndmask_b32_e64 v94, v94, v232, s[66:67]
	v_cndmask_b32_e64 v93, v93, v232, s[64:65]
	v_cndmask_b32_e64 v92, v92, v232, s[62:63]
	v_cndmask_b32_e64 v91, v91, v232, s[60:61]
	v_cndmask_b32_e64 v90, v90, v232, s[58:59]
	v_cndmask_b32_e64 v89, v89, v232, s[56:57]
	v_cndmask_b32_e64 v88, v88, v232, s[54:55]
	v_cndmask_b32_e64 v87, v87, v232, s[52:53]
	v_cndmask_b32_e64 v86, v86, v232, s[50:51]
	v_cndmask_b32_e64 v85, v85, v232, s[48:49]
	v_cndmask_b32_e64 v84, v84, v232, s[46:47]
	v_cndmask_b32_e64 v83, v83, v232, s[44:45]
	v_cndmask_b32_e64 v82, v82, v232, s[42:43]
	v_cndmask_b32_e64 v81, v81, v232, s[38:39]
	v_cndmask_b32_e64 v79, v79, v232, s[36:37]
	v_cndmask_b32_e64 v78, v78, v232, s[34:35]
	v_cndmask_b32_e64 v77, v77, v232, s[30:31]
	v_cndmask_b32_e64 v76, v76, v232, s[28:29]
	v_cndmask_b32_e64 v75, v75, v232, s[26:27]
	v_cndmask_b32_e64 v74, v74, v232, s[24:25]
	v_cndmask_b32_e64 v73, v73, v232, s[22:23]
	v_cndmask_b32_e64 v72, v72, v232, s[20:21]
	v_cndmask_b32_e64 v71, v71, v232, s[18:19]
	v_cndmask_b32_e64 v70, v70, v232, s[16:17]
	v_cndmask_b32_e64 v69, v69, v232, s[14:15]
	v_cndmask_b32_e64 v68, v68, v232, s[12:13]
	v_cndmask_b32_e64 v67, v67, v232, s[10:11]
	v_cndmask_b32_e64 v66, v66, v232, s[8:9]
	v_cndmask_b32_e64 v65, v65, v232, s[6:7]
	v_cndmask_b32_e32 v64, v64, v232, vcc
.LBB0_1356:
	v_max_f32_e32 v146, v81, v81
	v_max_f32_e32 v147, v80, v80
	v_max_f32_e32 v146, v147, v146
	v_max3_f32 v146, v146, v82, v83
	v_max3_f32 v146, v146, v84, v85
	v_max3_f32 v146, v146, v86, v87
	v_max3_f32 v146, v146, v88, v89
	v_max3_f32 v146, v146, v90, v91
	v_max3_f32 v146, v146, v92, v93
	v_max3_f32 v146, v146, v94, v95
	v_max3_f32 v146, v146, v64, v65
	v_max3_f32 v146, v146, v66, v67
	v_max3_f32 v146, v146, v68, v69
	v_max3_f32 v146, v146, v70, v71
	v_max3_f32 v146, v146, v72, v73
	v_max3_f32 v146, v146, v74, v75
	v_max3_f32 v146, v146, v76, v77
	v_max3_f32 v146, v146, v78, v79
	v_mov_b32_e32 v147, v146
	s_nop 1
	v_permlane32_swap_b32_e32 v146, v147
	v_max_f32_e32 v147, v147, v147
	v_max_f32_e32 v146, v146, v146
	v_max_f32_e32 v146, v146, v147
	v_sub_f32_e32 v147, v146, v194
	v_mul_f32_e32 v147, 0x3db504f3, v147
	s_mov_b32 s6, 0x41000000
	v_cmp_ge_f32_e32 vcc, s6, v147
	v_max_f32_e32 v147, v194, v194
	v_max_f32_e32 v146, v147, v146
	v_sub_f32_e32 v147, v194, v146
	v_mul_f32_e32 v147, 0x3e0293ee, v147
	v_exp_f32_e32 v147, v147
	s_cmp_eq_u64 vcc, exec
	s_cselect_b64 s[6:7], -1, 0
	s_barrier
	s_waitcnt vmcnt(0)
	v_cndmask_b32_e64 v197, v147, 1.0, s[6:7]
	v_cmp_gt_f32_e32 vcc, 1.0, v197
	s_waitcnt vmcnt(0)
	ds_write_b128 v189, v[242:245]
	ds_write_b128 v190, v[246:249]
	s_cbranch_vccz .LBB0_1360
	s_and_saveexec_b64 s[8:9], s[4:5]
	ds_write_b32 v182, v197 offset:128
	s_or_b64 exec, exec, s[8:9]
	s_waitcnt lgkmcnt(0)
	ds_read_b128 v[148:151], v165 offset:224
	ds_read_b128 v[152:155], v165 offset:192
	ds_read_b128 v[156:159], v165 offset:160
	ds_read_b128 v[198:201], v165 offset:128
	s_waitcnt lgkmcnt(3)
	v_pk_mul_f32 v[62:63], v[62:63], v[150:151]
	s_waitcnt lgkmcnt(2)
	v_pk_mul_f32 v[58:59], v[58:59], v[154:155]
	s_waitcnt lgkmcnt(1)
	v_pk_mul_f32 v[54:55], v[54:55], v[158:159]
	s_waitcnt lgkmcnt(0)
	v_pk_mul_f32 v[50:51], v[50:51], v[200:201]
	v_pk_mul_f32 v[60:61], v[60:61], v[148:149]
	v_pk_mul_f32 v[56:57], v[56:57], v[152:153]
	v_pk_mul_f32 v[52:53], v[52:53], v[156:157]
	v_pk_mul_f32 v[48:49], v[48:49], v[198:199]
	v_pk_mul_f32 v[46:47], v[46:47], v[150:151]
	v_pk_mul_f32 v[42:43], v[42:43], v[154:155]
	v_pk_mul_f32 v[38:39], v[38:39], v[158:159]
	v_pk_mul_f32 v[34:35], v[34:35], v[200:201]
	v_pk_mul_f32 v[44:45], v[44:45], v[148:149]
	v_pk_mul_f32 v[40:41], v[40:41], v[152:153]
	v_pk_mul_f32 v[36:37], v[36:37], v[156:157]
	v_pk_mul_f32 v[32:33], v[32:33], v[198:199]
	v_pk_mul_f32 v[30:31], v[30:31], v[150:151]
	v_pk_mul_f32 v[26:27], v[26:27], v[154:155]
	v_pk_mul_f32 v[22:23], v[22:23], v[158:159]
	v_pk_mul_f32 v[18:19], v[18:19], v[200:201]
	v_pk_mul_f32 v[28:29], v[28:29], v[148:149]
	v_pk_mul_f32 v[24:25], v[24:25], v[152:153]
	v_pk_mul_f32 v[20:21], v[20:21], v[156:157]
	v_pk_mul_f32 v[16:17], v[16:17], v[198:199]
	v_pk_mul_f32 v[14:15], v[14:15], v[150:151]
	v_pk_mul_f32 v[10:11], v[10:11], v[154:155]
	v_pk_mul_f32 v[6:7], v[6:7], v[158:159]
	v_pk_mul_f32 v[2:3], v[2:3], v[200:201]
	v_pk_mul_f32 v[12:13], v[12:13], v[148:149]
	v_pk_mul_f32 v[8:9], v[8:9], v[152:153]
	v_pk_mul_f32 v[4:5], v[4:5], v[156:157]
	v_pk_mul_f32 v[0:1], v[0:1], v[198:199]

.LBB0_1518:
	v_readfirstlane_b32 s8, v186
	v_lshrrev_b32_e32 v234, 4, v186
	v_lshl_add_u64 v[230:231], v[172:173], 0, v[96:97]
	s_and_b32 s8, s8, 0xfffffc00
	v_and_b32_e32 v234, 0x70, v234
	s_add_i32 m0, s8, 0x8000
	v_xor_b32_e32 v230, v234, v230
	v_lshl_add_u64 v[242:243], v[170:171], 0, v[96:97]
	global_load_lds_dwordx4 v[230:231], off
	v_lshl_add_u64 v[230:231], v[168:169], 0, v[96:97]
	s_add_i32 m0, s8, 0xa000
	v_xor_b32_e32 v230, v234, v230
	v_lshl_add_u64 v[246:247], v[166:167], 0, v[96:97]
	global_load_lds_dwordx4 v[230:231], off
	global_load_dwordx4 v[242:245], v[242:243], off
	global_load_dwordx4 v[246:249], v[246:247], off
	ds_read_b128 v[80:83], v200
	ds_read_b128 v[84:87], v200 offset:32
	ds_read_b128 v[64:67], v200 offset:128
	ds_read_b128 v[68:71], v200 offset:160
	ds_read_b128 v[88:91], v200 offset:64
	ds_read_b128 v[72:75], v200 offset:192
	ds_read_b128 v[92:95], v200 offset:96
	ds_read_b128 v[76:79], v200 offset:224
	ds_read_b128 v[208:211], v194 offset:49152
	ds_read_b128 v[220:223], v194 offset:57344
	v_add_f32_e32 v146, 0, v147
	v_add_f32_e32 v146, v148, v146
	v_add_f32_e32 v146, v149, v146
	s_waitcnt lgkmcnt(1)
	v_mfma_f32_32x32x16_bf16 v[80:95], v[208:211], v[126:129], v[80:95]
	v_add_f32_e32 v146, v160, v146
	v_add_f32_e32 v146, v161, v146
	v_add_f32_e32 v146, v207, v146
	v_add_f32_e32 v146, v159, v146
	v_add_f32_e32 v146, v206, v146
	v_add_f32_e32 v146, v151, v146
	v_add_f32_e32 v146, v153, v146
	s_waitcnt lgkmcnt(0)
	v_mfma_f32_32x32x16_bf16 v[64:79], v[220:223], v[126:129], v[64:79]
	ds_read_b128 v[208:211], v195 offset:49152
	ds_read_b128 v[220:223], v195 offset:57344
	v_add_f32_e32 v146, v154, v146
	v_add_f32_e32 v146, v155, v146
	v_exp_f32_e32 v144, v144
	v_add_f32_e32 v146, v152, v146
	v_exp_f32_e32 v145, v145
	v_add_f32_e32 v146, v156, v146
	s_waitcnt lgkmcnt(1)
	v_mfma_f32_32x32x16_bf16 v[80:95], v[208:211], v[122:125], v[80:95]
	v_exp_f32_e32 v142, v142
	v_add_f32_e32 v146, v157, v146
	v_exp_f32_e32 v143, v143
	v_add_f32_e32 v146, v158, v146
	v_exp_f32_e32 v140, v140
	v_add_f32_e32 v146, v144, v146
	v_exp_f32_e32 v141, v141
	s_waitcnt lgkmcnt(0)
	v_mfma_f32_32x32x16_bf16 v[64:79], v[220:223], v[122:125], v[64:79]
	ds_read_b128 v[208:211], v193 offset:49152
	ds_read_b128 v[220:223], v193 offset:57344
	v_add_f32_e32 v146, v145, v146
	v_exp_f32_e32 v138, v138
	v_add_f32_e32 v146, v142, v146
	v_exp_f32_e32 v139, v139
	v_add_f32_e32 v146, v143, v146
	v_exp_f32_e32 v136, v136
	s_waitcnt lgkmcnt(1)
	v_mfma_f32_32x32x16_bf16 v[80:95], v[208:211], v[118:121], v[80:95]
	v_add_f32_e32 v146, v140, v146
	v_exp_f32_e32 v137, v137
	v_add_f32_e32 v146, v141, v146
	v_exp_f32_e32 v134, v134
	v_add_f32_e32 v146, v138, v146
	v_exp_f32_e32 v135, v135
	v_add_f32_e32 v146, v139, v146
	s_waitcnt lgkmcnt(0)
	v_mfma_f32_32x32x16_bf16 v[64:79], v[220:223], v[118:121], v[64:79]
	ds_read_b128 v[208:211], v192 offset:49152
	ds_read_b128 v[220:223], v192 offset:57344
	v_exp_f32_e32 v132, v132
	v_add_f32_e32 v146, v136, v146
	v_exp_f32_e32 v133, v133
	v_add_f32_e32 v146, v137, v146
	v_exp_f32_e32 v130, v130
	v_add_f32_e32 v146, v134, v146
	s_waitcnt lgkmcnt(1)
	v_mfma_f32_32x32x16_bf16 v[80:95], v[208:211], v[114:117], v[80:95]
	v_exp_f32_e32 v131, v131
	v_add_f32_e32 v146, v135, v146
	v_add_f32_e32 v146, v132, v146
	v_add_f32_e32 v146, v133, v146
	v_add_f32_e32 v146, v130, v146
	v_add_f32_e32 v203, v131, v146
	v_mov_b32_e32 v204, v203
	s_waitcnt lgkmcnt(0)
	v_mfma_f32_32x32x16_bf16 v[64:79], v[220:223], v[114:117], v[64:79]
	ds_read_b128 v[208:211], v194 offset:49280
	ds_read_b128 v[220:223], v194 offset:57472
	v_permlane32_swap_b32_e32 v203, v204
	v_cvt_pk_bf16_f32 v146, v147, v148
	v_cvt_pk_bf16_f32 v147, v149, v160
	v_cvt_pk_bf16_f32 v148, v161, v207
	v_cvt_pk_bf16_f32 v149, v159, v206
	s_waitcnt lgkmcnt(1)
	v_mfma_f32_32x32x16_bf16 v[80:95], v[208:211], v[110:113], v[80:95]
	v_cvt_pk_bf16_f32 v206, v151, v153
	v_cvt_pk_bf16_f32 v207, v154, v155
	v_cvt_pk_bf16_f32 v153, v142, v143
	v_cvt_pk_bf16_f32 v154, v140, v141
	v_cvt_pk_bf16_f32 v155, v138, v139
	v_cvt_pk_bf16_f32 v159, v130, v131
	v_permlane32_swap_b32_e32 v146, v148
	s_waitcnt lgkmcnt(0)
	v_mfma_f32_32x32x16_bf16 v[64:79], v[220:223], v[110:113], v[64:79]
	ds_read_b128 v[208:211], v195 offset:49280
	ds_read_b128 v[220:223], v195 offset:57472
	v_permlane32_swap_b32_e32 v147, v149
	v_permlane32_swap_b32_e32 v153, v155
	s_waitcnt lgkmcnt(1)
	v_mfma_f32_32x32x16_bf16 v[80:95], v[208:211], v[106:109], v[80:95]
	s_waitcnt lgkmcnt(0)
	v_mfma_f32_32x32x16_bf16 v[64:79], v[220:223], v[106:109], v[64:79]
	ds_read_b128 v[208:211], v193 offset:49280
	ds_read_b128 v[220:223], v193 offset:57472
	s_waitcnt lgkmcnt(1)
	v_mfma_f32_32x32x16_bf16 v[80:95], v[208:211], v[102:105], v[80:95]
	s_waitcnt lgkmcnt(0)
	v_mfma_f32_32x32x16_bf16 v[64:79], v[220:223], v[102:105], v[64:79]
	ds_read_b128 v[208:211], v192 offset:49280
	ds_read_b128 v[220:223], v192 offset:57472
	s_waitcnt lgkmcnt(1)
	v_mfma_f32_32x32x16_bf16 v[80:95], v[208:211], v[98:101], v[80:95]
	v_cvt_pk_bf16_f32 v208, v152, v156
	v_cvt_pk_bf16_f32 v209, v157, v158
	v_cvt_pk_bf16_f32 v152, v144, v145
	v_cvt_pk_bf16_f32 v156, v136, v137
	v_cvt_pk_bf16_f32 v157, v134, v135
	v_cvt_pk_bf16_f32 v158, v132, v133
	v_permlane32_swap_b32_e32 v206, v208
	s_waitcnt lgkmcnt(0)
	v_mfma_f32_32x32x16_bf16 v[64:79], v[220:223], v[98:101], v[64:79]
	v_permlane32_swap_b32_e32 v207, v209
	v_permlane32_swap_b32_e32 v152, v154
	v_permlane32_swap_b32_e32 v156, v158
	v_permlane32_swap_b32_e32 v157, v159
	ds_read_b64_tr_b16 v[210:211], v188 offset:0
	ds_read_b64_tr_b16 v[212:213], v188 offset:0x800
	ds_read_b64_tr_b16 v[220:221], v188 offset:0x1000
	ds_read_b64_tr_b16 v[222:223], v188 offset:0x1800
	ds_read_b64_tr_b16 v[224:225], v188 offset:0x2000
	ds_read_b64_tr_b16 v[226:227], v188 offset:0x2800
	ds_read_b64_tr_b16 v[238:239], v188 offset:0x3000
	ds_read_b64_tr_b16 v[240:241], v188 offset:0x3800
	s_waitcnt lgkmcnt(0)
	s_nop 0
	v_mfma_f32_32x32x16_bf16 v[0:15], v[146:149], v[210:213], v[0:15]
	ds_read_b64_tr_b16 v[210:211], v188 offset:0x200
	ds_read_b64_tr_b16 v[212:213], v188 offset:0xa00
	v_mfma_f32_32x32x16_bf16 v[0:15], v[206:209], v[220:223], v[0:15]
	ds_read_b64_tr_b16 v[220:221], v188 offset:0x1200
	ds_read_b64_tr_b16 v[222:223], v188 offset:0x1a00
	v_mfma_f32_32x32x16_bf16 v[0:15], v[152:155], v[224:227], v[0:15]
	ds_read_b64_tr_b16 v[224:225], v188 offset:0x2200
	ds_read_b64_tr_b16 v[226:227], v188 offset:0x2a00
	v_mfma_f32_32x32x16_bf16 v[0:15], v[156:159], v[238:241], v[0:15]
	ds_read_b64_tr_b16 v[238:239], v188 offset:0x3200
	ds_read_b64_tr_b16 v[240:241], v188 offset:0x3a00
	s_waitcnt lgkmcnt(0)
	v_mfma_f32_32x32x16_bf16 v[48:63], v[146:149], v[210:213], v[48:63]
	ds_read_b64_tr_b16 v[210:211], v188 offset:0x400
	ds_read_b64_tr_b16 v[212:213], v188 offset:0xc00
	v_mfma_f32_32x32x16_bf16 v[48:63], v[206:209], v[220:223], v[48:63]
	ds_read_b64_tr_b16 v[220:221], v188 offset:0x1400
	ds_read_b64_tr_b16 v[222:223], v188 offset:0x1c00
	v_mfma_f32_32x32x16_bf16 v[48:63], v[152:155], v[224:227], v[48:63]
	ds_read_b64_tr_b16 v[224:225], v188 offset:0x2400
	ds_read_b64_tr_b16 v[226:227], v188 offset:0x2c00
	v_mfma_f32_32x32x16_bf16 v[48:63], v[156:159], v[238:241], v[48:63]
	ds_read_b64_tr_b16 v[238:239], v188 offset:0x3400
	ds_read_b64_tr_b16 v[240:241], v188 offset:0x3c00
	s_waitcnt lgkmcnt(0)
	v_mfma_f32_32x32x16_bf16 v[32:47], v[146:149], v[210:213], v[32:47]
	ds_read_b64_tr_b16 v[210:211], v188 offset:0x600
	ds_read_b64_tr_b16 v[212:213], v188 offset:0xe00
	v_mfma_f32_32x32x16_bf16 v[32:47], v[206:209], v[220:223], v[32:47]
	ds_read_b64_tr_b16 v[220:221], v188 offset:0x1600
	ds_read_b64_tr_b16 v[222:223], v188 offset:0x1e00
	v_mfma_f32_32x32x16_bf16 v[32:47], v[152:155], v[224:227], v[32:47]
	ds_read_b64_tr_b16 v[224:225], v188 offset:0x2600
	ds_read_b64_tr_b16 v[226:227], v188 offset:0x2e00
	v_mfma_f32_32x32x16_bf16 v[32:47], v[156:159], v[238:241], v[32:47]
	ds_read_b64_tr_b16 v[238:239], v188 offset:0x3600
	ds_read_b64_tr_b16 v[240:241], v188 offset:0x3e00
	s_waitcnt lgkmcnt(0)
	v_mfma_f32_32x32x16_bf16 v[16:31], v[146:149], v[210:213], v[16:31]
	s_sub_i32 s6, s74, 64
	s_cmp_le_i32 s6, s3
	v_mfma_f32_32x32x16_bf16 v[16:31], v[206:209], v[220:223], v[16:31]
	v_mfma_f32_32x32x16_bf16 v[16:31], v[152:155], v[224:227], v[16:31]
	v_mfma_f32_32x32x16_bf16 v[16:31], v[156:159], v[238:241], v[16:31]
	s_cbranch_scc1 .LBB0_1520
	v_add_u32_e32 v146, 64, v202
	v_cmp_gt_i32_e64 s[66:67], 26, v146
	v_cmp_gt_i32_e64 s[68:69], 27, v146
	v_cmp_gt_i32_e64 s[64:65], 25, v146
	s_and_b64 s[66:67], s[68:69], s[66:67]
	v_cmp_gt_i32_e64 s[62:63], 24, v146
	s_and_b64 s[64:65], s[66:67], s[64:65]
	v_cmp_gt_i32_e64 s[60:61], 19, v146
	s_and_b64 s[62:63], s[64:65], s[62:63]
	v_cmp_gt_i32_e64 s[58:59], 18, v146
	s_and_b64 s[60:61], s[62:63], s[60:61]
	v_cmp_gt_i32_e64 s[56:57], 17, v146
	s_and_b64 s[58:59], s[60:61], s[58:59]
	v_cmp_gt_i32_e64 s[54:55], 16, v146
	s_and_b64 s[56:57], s[58:59], s[56:57]
	v_cmp_gt_i32_e64 s[52:53], 11, v146
	s_and_b64 s[54:55], s[56:57], s[54:55]
	v_cmp_gt_i32_e64 s[50:51], 10, v146
	s_and_b64 s[52:53], s[54:55], s[52:53]
	v_cmp_gt_i32_e64 s[48:49], 9, v146
	s_and_b64 s[50:51], s[52:53], s[50:51]
	v_cmp_gt_i32_e64 s[46:47], 8, v146
	s_and_b64 s[48:49], s[50:51], s[48:49]
	v_cmp_gt_i32_e64 s[44:45], 3, v146
	s_and_b64 s[46:47], s[48:49], s[46:47]
	v_cmp_gt_i32_e64 s[42:43], 2, v146
	s_and_b64 s[44:45], s[46:47], s[44:45]
	v_cmp_gt_i32_e64 s[38:39], 1, v146
	s_and_b64 s[42:43], s[44:45], s[42:43]
	v_cmp_gt_i32_e64 s[36:37], 0, v146
	s_and_b64 s[38:39], s[42:43], s[38:39]
	s_and_b64 s[36:37], s[38:39], s[36:37]
	v_cmp_gt_i32_e64 s[34:35], 58, v146
	v_cndmask_b32_e64 v80, v80, v232, s[36:37]
	v_cmp_gt_i32_e64 s[36:37], 59, v146
	v_cmp_gt_i32_e64 s[30:31], 57, v146
	s_and_b64 s[34:35], s[36:37], s[34:35]
	v_cmp_gt_i32_e64 s[28:29], 56, v146
	s_and_b64 s[30:31], s[34:35], s[30:31]
	v_cmp_gt_i32_e64 s[26:27], 51, v146
	s_and_b64 s[28:29], s[30:31], s[28:29]
	v_cmp_gt_i32_e64 s[24:25], 50, v146
	s_and_b64 s[26:27], s[28:29], s[26:27]
	v_cmp_gt_i32_e64 s[22:23], 49, v146
	s_and_b64 s[24:25], s[26:27], s[24:25]
	v_cmp_gt_i32_e64 s[20:21], 48, v146
	s_and_b64 s[22:23], s[24:25], s[22:23]
	v_cmp_gt_i32_e64 s[18:19], 43, v146
	s_and_b64 s[20:21], s[22:23], s[20:21]
	v_cmp_gt_i32_e64 s[16:17], 42, v146
	s_and_b64 s[18:19], s[20:21], s[18:19]
	v_cmp_gt_i32_e64 s[14:15], 41, v146
	s_and_b64 s[16:17], s[18:19], s[16:17]
	v_cmp_gt_i32_e64 s[12:13], 40, v146
	s_and_b64 s[14:15], s[16:17], s[14:15]
	v_cmp_gt_i32_e64 s[10:11], 35, v146
	s_and_b64 s[12:13], s[14:15], s[12:13]
	v_cmp_gt_i32_e64 s[8:9], 34, v146
	s_and_b64 s[10:11], s[12:13], s[10:11]
	v_cmp_gt_i32_e64 s[6:7], 33, v146
	s_and_b64 s[8:9], s[10:11], s[8:9]
	v_cmp_gt_i32_e32 vcc, 32, v146
	s_and_b64 s[6:7], s[8:9], s[6:7]
	s_and_b64 vcc, s[6:7], vcc
	v_cndmask_b32_e64 v95, v95, v232, s[68:69]
	v_cndmask_b32_e64 v94, v94, v232, s[66:67]
	v_cndmask_b32_e64 v93, v93, v232, s[64:65]
	v_cndmask_b32_e64 v92, v92, v232, s[62:63]
	v_cndmask_b32_e64 v91, v91, v232, s[60:61]
	v_cndmask_b32_e64 v90, v90, v232, s[58:59]
	v_cndmask_b32_e64 v89, v89, v232, s[56:57]
	v_cndmask_b32_e64 v88, v88, v232, s[54:55]
	v_cndmask_b32_e64 v87, v87, v232, s[52:53]
	v_cndmask_b32_e64 v86, v86, v232, s[50:51]
	v_cndmask_b32_e64 v85, v85, v232, s[48:49]
	v_cndmask_b32_e64 v84, v84, v232, s[46:47]
	v_cndmask_b32_e64 v83, v83, v232, s[44:45]
	v_cndmask_b32_e64 v82, v82, v232, s[42:43]
	v_cndmask_b32_e64 v81, v81, v232, s[38:39]
	v_cndmask_b32_e64 v79, v79, v232, s[36:37]
	v_cndmask_b32_e64 v78, v78, v232, s[34:35]
	v_cndmask_b32_e64 v77, v77, v232, s[30:31]
	v_cndmask_b32_e64 v76, v76, v232, s[28:29]
	v_cndmask_b32_e64 v75, v75, v232, s[26:27]
	v_cndmask_b32_e64 v74, v74, v232, s[24:25]
	v_cndmask_b32_e64 v73, v73, v232, s[22:23]
	v_cndmask_b32_e64 v72, v72, v232, s[20:21]
	v_cndmask_b32_e64 v71, v71, v232, s[18:19]
	v_cndmask_b32_e64 v70, v70, v232, s[16:17]
	v_cndmask_b32_e64 v69, v69, v232, s[14:15]
	v_cndmask_b32_e64 v68, v68, v232, s[12:13]
	v_cndmask_b32_e64 v67, v67, v232, s[10:11]
	v_cndmask_b32_e64 v66, v66, v232, s[8:9]
	v_cndmask_b32_e64 v65, v65, v232, s[6:7]
	v_cndmask_b32_e32 v64, v64, v232, vcc
.LBB0_1520:
	v_max_f32_e32 v146, v81, v81
	v_max_f32_e32 v147, v80, v80
	v_max_f32_e32 v146, v147, v146
	v_max3_f32 v146, v146, v82, v83
	v_max3_f32 v146, v146, v84, v85
	v_max3_f32 v146, v146, v86, v87
	v_max3_f32 v146, v146, v88, v89
	v_max3_f32 v146, v146, v90, v91
	v_max3_f32 v146, v146, v92, v93
	v_max3_f32 v146, v146, v94, v95
	v_max3_f32 v146, v146, v64, v65
	v_max3_f32 v146, v146, v66, v67
	v_max3_f32 v146, v146, v68, v69
	v_max3_f32 v146, v146, v70, v71
	v_max3_f32 v146, v146, v72, v73
	v_max3_f32 v146, v146, v74, v75
	v_max3_f32 v146, v146, v76, v77
	v_max3_f32 v146, v146, v78, v79
	v_mov_b32_e32 v147, v146
	s_nop 1
	v_permlane32_swap_b32_e32 v146, v147
	v_max_f32_e32 v147, v147, v147
	v_max_f32_e32 v146, v146, v146
	v_max_f32_e32 v146, v146, v147
	v_sub_f32_e32 v147, v146, v150
	v_mul_f32_e32 v147, 0x3db504f3, v147
	s_mov_b32 s6, 0x41000000
	v_cmp_ge_f32_e32 vcc, s6, v147
	v_max_f32_e32 v147, v150, v150
	v_max_f32_e32 v146, v147, v146
	v_sub_f32_e32 v147, v150, v146
	v_mul_f32_e32 v147, 0x3e0293ee, v147
	v_exp_f32_e32 v147, v147
	s_cmp_eq_u64 vcc, exec
	s_cselect_b64 s[6:7], -1, 0
	s_barrier
	s_waitcnt vmcnt(0)
	v_cndmask_b32_e64 v205, v147, 1.0, s[6:7]
	v_cmp_gt_f32_e32 vcc, 1.0, v205
	s_waitcnt vmcnt(0)
	ds_write_b128 v197, v[242:245]
	ds_write_b128 v198, v[246:249]
	s_cbranch_vccz .LBB0_1524
	s_and_saveexec_b64 s[8:9], s[4:5]
	ds_write_b32 v201, v205 offset:128
	s_or_b64 exec, exec, s[8:9]
	s_waitcnt lgkmcnt(0)
	ds_read_b128 v[152:155], v191 offset:224
	ds_read_b128 v[156:159], v191 offset:192
	ds_read_b128 v[206:209], v191 offset:160
	ds_read_b128 v[210:213], v191 offset:128
	s_waitcnt lgkmcnt(3)
	v_pk_mul_f32 v[14:15], v[14:15], v[154:155]
	s_waitcnt lgkmcnt(2)
	v_pk_mul_f32 v[10:11], v[10:11], v[158:159]
	s_waitcnt lgkmcnt(1)
	v_pk_mul_f32 v[6:7], v[6:7], v[208:209]
	s_waitcnt lgkmcnt(0)
	v_pk_mul_f32 v[2:3], v[2:3], v[212:213]
	v_pk_mul_f32 v[12:13], v[12:13], v[152:153]
	v_pk_mul_f32 v[8:9], v[8:9], v[156:157]
	v_pk_mul_f32 v[4:5], v[4:5], v[206:207]
	v_pk_mul_f32 v[0:1], v[0:1], v[210:211]
	v_pk_mul_f32 v[62:63], v[62:63], v[154:155]
	v_pk_mul_f32 v[58:59], v[58:59], v[158:159]
	v_pk_mul_f32 v[54:55], v[54:55], v[208:209]
	v_pk_mul_f32 v[50:51], v[50:51], v[212:213]
	v_pk_mul_f32 v[60:61], v[60:61], v[152:153]
	v_pk_mul_f32 v[56:57], v[56:57], v[156:157]
	v_pk_mul_f32 v[52:53], v[52:53], v[206:207]
	v_pk_mul_f32 v[48:49], v[48:49], v[210:211]
	v_pk_mul_f32 v[46:47], v[46:47], v[154:155]
	v_pk_mul_f32 v[42:43], v[42:43], v[158:159]
	v_pk_mul_f32 v[38:39], v[38:39], v[208:209]
	v_pk_mul_f32 v[34:35], v[34:35], v[212:213]
	v_pk_mul_f32 v[44:45], v[44:45], v[152:153]
	v_pk_mul_f32 v[40:41], v[40:41], v[156:157]
	v_pk_mul_f32 v[36:37], v[36:37], v[206:207]
	v_pk_mul_f32 v[32:33], v[32:33], v[210:211]
	v_pk_mul_f32 v[30:31], v[30:31], v[154:155]
	v_pk_mul_f32 v[26:27], v[26:27], v[158:159]
	v_pk_mul_f32 v[22:23], v[22:23], v[208:209]
	v_pk_mul_f32 v[18:19], v[18:19], v[212:213]
	v_pk_mul_f32 v[28:29], v[28:29], v[152:153]
	v_pk_mul_f32 v[24:25], v[24:25], v[156:157]
	v_pk_mul_f32 v[20:21], v[20:21], v[206:207]
	v_pk_mul_f32 v[16:17], v[16:17], v[210:211]
